# combination: DSA parking/exchange addresses kept in registers, FoX back-edge rotation, packed oacc rescale split, on top of the gate-epilogue version
# speedup vs baseline: 1.0053x; 1.0053x over previous
; #define LAS __attribute__((address_space(3)))
; __device__ __forceinline__ u16 f2bf(float f) { return (u16)(cvtpk(f, 0.f) & 0xffffu); }
;     ...
;           float mx = fmaxf(fmaxf(lgv[0], lgv[1]), fmaxf(lgv[2], lgv[3]));
; #pragma unroll
;           for (int o = 1; o < 16; o <<= 1) mx = fmaxf(mx, __shfl_xor(mx, o));
;           const float mnew = fmaxf(mrun, mx), alpha = __expf(mrun - mnew); mrun = mnew;
;           float ps = 0.f;
; #pragma unroll
;           for (int jj = 0; jj < 4; ++jj) { const float pe = __expf(lgv[jj] - mnew); ps += pe; pbT[quad * 64 + jj * 16 + c16] = f2bf(pe * rsv[jj]); }
;           lsum = lsum * alpha + ps;
;           if (c16 == 0) alf[quad] = alpha;
;           const f32x4 al4 = *(const LAS f32x4*)alf;
; #pragma unroll
;           for (int c = 0; c < 8; ++c) oacc[c] *= al4;
; #pragma unroll
;           for (int ks = 0; ks < 2; ++ks) {
;               const bf16x8 pf = *(const LAS bf16x8*)(pbT + (c16 & 3) * 64 + ks * 32 + quad * 8);
;               u16x4 t0[8], t1[8];
;     ...
;               if (ks == 0) { TRR8(t0, 0, 0); TRR8(t1, 1, 0); } else { TRR8(t0, 0, 8192); TRR8(t1, 1, 8192); }
;     ...
; #pragma unroll
;               for (int c = 0; c < 8; ++c) {
;                   const bf16x8 bf = {(short)t0[c][0], (short)t0[c][1], (short)t0[c][2], (short)t0[c][3], (short)t1[c][0], (short)t1[c][1], (short)t1[c][2], (short)t1[c][3]};
;                   oacc[c] = __builtin_amdgcn_mfma_f32_16x16x32_bf16(pf, bf, oacc[c], 0, 0, 0);
;               }
;           }
.LBB0_946:
	s_waitcnt lgkmcnt(1)
	v_add_f32_e32 v119, v119, v175
	v_add_f32_e32 v117, v117, v174
	v_add_f32_e32 v115, v115, v173
	v_add_f32_e32 v0, v161, v172
	v_fmamk_f32 v119, v119, 0x3c000000, v199
	v_fmamk_f32 v117, v117, 0x3c000000, v199
	v_fmamk_f32 v115, v115, 0x3c000000, v199
	v_fmamk_f32 v0, v0, 0x3c000000, v199
	v_rsq_f32_e32 v122, v119
	v_rsq_f32_e32 v123, v117
	v_rsq_f32_e32 v125, v115
	v_rsq_f32_e32 v161, v0
	v_add_u32_e32 v0, 48, v157
	v_add_u32_e32 v115, 32, v157
	v_mul_f32_e32 v119, v122, v120
	v_cmp_gt_i32_e32 vcc, s22, v0
	v_mul_f32_e32 v117, v123, v118
	v_mul_f32_e32 v119, 0x3db504f3, v119
	v_cndmask_b32_e32 v121, v208, v119, vcc
	v_cmp_gt_i32_e32 vcc, s22, v115
	v_mul_f32_e32 v117, 0x3db504f3, v117
	v_add_u32_e32 v0, 16, v157
	v_cndmask_b32_e32 v120, v208, v117, vcc
	v_mul_f32_e32 v119, v125, v116
	v_cmp_gt_i32_e32 vcc, s22, v0
	v_mul_f32_e32 v119, 0x3db504f3, v119
	v_mul_f32_e32 v0, v161, v114
	v_cndmask_b32_e32 v119, v208, v119, vcc
	v_cmp_gt_i32_e32 vcc, s22, v157
	v_mul_f32_e32 v0, 0x3db504f3, v0
	s_nop 0
	v_cndmask_b32_e32 v118, v208, v0, vcc
	v_max_f32_e32 v0, v120, v121
	v_max3_f32 v114, v118, v119, v0
	s_nop 1
	v_max_f32_dpp v115, v114, v114 quad_perm:[1,0,3,2] row_mask:0xf bank_mask:0xf
	s_nop 1
	v_max_f32_dpp v116, v115, v115 quad_perm:[2,3,0,1] row_mask:0xf bank_mask:0xf
	s_nop 1
	v_max_f32_dpp v117, v116, v116 row_ror:4 row_mask:0xf bank_mask:0xf
	s_nop 1
	v_max_f32_dpp v172, v117, v117 row_ror:8 row_mask:0xf bank_mask:0xf
	v_max3_f32 v117, v160, v117, v172
	v_sub_f32_e32 v118, v118, v117
	v_sub_f32_e32 v119, v119, v117
	v_sub_f32_e32 v120, v120, v117
	v_sub_f32_e32 v121, v121, v117
	v_mul_f32_e32 v118, 0x3fb8aa3b, v118
	v_mul_f32_e32 v119, 0x3fb8aa3b, v119
	v_mul_f32_e32 v120, 0x3fb8aa3b, v120
	v_mul_f32_e32 v121, 0x3fb8aa3b, v121
	v_exp_f32_e32 v118, v118
	v_exp_f32_e32 v119, v119
	v_exp_f32_e32 v120, v120
	v_exp_f32_e32 v121, v121
	v_sub_f32_e32 v160, v160, v117
	v_mul_f32_e32 v161, v161, v118
	v_mul_f32_e32 v125, v125, v119
	v_mul_f32_e32 v123, v123, v120
	v_mul_f32_e32 v122, v122, v121
	v_mul_f32_e32 v160, 0x3fb8aa3b, v160
	v_cvt_pk_bf16_f32 v161, v161, v1
	ds_write_b16 v155, v161 offset:1024
	v_cvt_pk_bf16_f32 v125, v125, v1
	ds_write_b16 v155, v125 offset:1056
	v_cvt_pk_bf16_f32 v123, v123, v1
	ds_write_b16 v155, v123 offset:1088
	v_cvt_pk_bf16_f32 v122, v122, v1
	ds_write_b16 v155, v122 offset:1120
	v_exp_f32_e32 v122, v160
	s_and_saveexec_b64 s[0:1], s[38:39]
	ds_write_b32 v129, v122 offset:640
	s_or_b64 exec, exec, s[0:1]
	v_add_f32_e32 v118, 0, v118
	v_add_f32_e32 v118, v119, v118
	v_add_f32_e32 v118, v120, v118
	v_add_f32_e32 v118, v121, v118
	v_mov_b32_e32 v119, s56
	v_fmac_f32_e32 v118, v159, v122
	ds_read_b128 v[120:123], v119 offset:640
	v_add_u32_e32 v154, 0x80, v154
	v_add_u32_e32 v157, 64, v157
	s_cmp_eq_u32 s23, s24
	s_waitcnt lgkmcnt(0)
	v_mul_f32_e32 v174, v92, v122
	v_mul_f32_e32 v175, v93, v123
	v_mul_f32_e32 v172, v90, v120
	v_mul_f32_e32 v173, v91, v121
	v_mul_f32_e32 v92, v96, v122
	v_mul_f32_e32 v93, v97, v123
	v_mul_f32_e32 v90, v94, v120
	v_mul_f32_e32 v91, v95, v121
	ds_read_b128 v[94:97], v156 offset:1024
	ds_read_b64_tr_b16 v[216:217], v130 offset:0
	ds_read_b64_tr_b16 v[218:219], v138 offset:0
	ds_read_b64_tr_b16 v[212:213], v131 offset:0
	ds_read_b64_tr_b16 v[214:215], v139 offset:0
	ds_read_b64_tr_b16 v[194:195], v132 offset:0
	ds_read_b64_tr_b16 v[196:197], v140 offset:0
	ds_read_b64_tr_b16 v[190:191], v133 offset:0
	ds_read_b64_tr_b16 v[192:193], v141 offset:0
	ds_read_b64_tr_b16 v[186:187], v134 offset:0
	ds_read_b64_tr_b16 v[188:189], v142 offset:0
	v_mul_f32_e32 v106, v106, v120
	v_mul_f32_e32 v107, v107, v121
	v_mul_f32_e32 v110, v110, v120
	v_mul_f32_e32 v111, v111, v121
	v_mul_f32_e32 v176, v82, v120
	v_mul_f32_e32 v177, v83, v121
	v_mul_f32_e32 v182, v86, v120
	v_mul_f32_e32 v183, v87, v121
	v_mul_f32_e32 v86, v102, v120
	v_mul_f32_e32 v87, v103, v121
	v_mul_f32_e32 v82, v98, v120
	v_mul_f32_e32 v83, v99, v121
	v_mul_f32_e32 v108, v108, v122
	v_mul_f32_e32 v109, v109, v123
	v_mul_f32_e32 v112, v112, v122
	v_mul_f32_e32 v113, v113, v123
	v_mul_f32_e32 v178, v84, v122
	v_mul_f32_e32 v179, v85, v123
	v_mul_f32_e32 v184, v88, v122
	v_mul_f32_e32 v185, v89, v123
	v_mul_f32_e32 v88, v104, v122
	v_mul_f32_e32 v89, v105, v123
	v_mul_f32_e32 v84, v100, v122
	v_mul_f32_e32 v85, v101, v123
	ds_read_b64_tr_b16 v[120:121], v135 offset:0
	ds_read_b64_tr_b16 v[122:123], v143 offset:0
	ds_read_b64_tr_b16 v[102:103], v136 offset:0
	ds_read_b64_tr_b16 v[104:105], v144 offset:0
	s_waitcnt lgkmcnt(12)
	v_mfma_f32_16x16x32_bf16 v[106:109], v[94:97], v[216:219], v[106:109]
	ds_read_b64_tr_b16 v[98:99], v137 offset:0
	ds_read_b64_tr_b16 v[100:101], v145 offset:0
	s_waitcnt lgkmcnt(12)
	v_mfma_f32_16x16x32_bf16 v[110:113], v[94:97], v[212:215], v[110:113]
	s_waitcnt lgkmcnt(10)
	v_mfma_f32_16x16x32_bf16 v[172:175], v[94:97], v[194:197], v[172:175]
	s_waitcnt lgkmcnt(8)
	v_mfma_f32_16x16x32_bf16 v[176:179], v[94:97], v[190:193], v[176:179]
	s_waitcnt lgkmcnt(6)
	v_mfma_f32_16x16x32_bf16 v[182:185], v[94:97], v[186:189], v[182:185]
	s_waitcnt lgkmcnt(4)
	v_mfma_f32_16x16x32_bf16 v[120:123], v[94:97], v[120:123], v[90:93]
	s_waitcnt lgkmcnt(2)
	v_mfma_f32_16x16x32_bf16 v[102:105], v[94:97], v[102:105], v[86:89]
	s_waitcnt lgkmcnt(0)
	v_mfma_f32_16x16x32_bf16 v[98:101], v[94:97], v[98:101], v[82:85]
	ds_read_b128 v[220:223], v156 offset:1088
	ds_read_b64_tr_b16 v[212:213], v130 offset:8192
	ds_read_b64_tr_b16 v[214:215], v138 offset:8192
	ds_read_b64_tr_b16 v[194:195], v131 offset:8192
	ds_read_b64_tr_b16 v[196:197], v139 offset:8192
	ds_read_b64_tr_b16 v[90:91], v132 offset:8192
	ds_read_b64_tr_b16 v[92:93], v140 offset:8192
	ds_read_b64_tr_b16 v[82:83], v133 offset:8192
	ds_read_b64_tr_b16 v[84:85], v141 offset:8192
	ds_read_b64_tr_b16 v[86:87], v134 offset:8192
	ds_read_b64_tr_b16 v[88:89], v142 offset:8192
	ds_read_b64_tr_b16 v[94:95], v135 offset:8192
	ds_read_b64_tr_b16 v[96:97], v143 offset:8192
	ds_read_b64_tr_b16 v[190:191], v136 offset:8192
	ds_read_b64_tr_b16 v[192:193], v144 offset:8192
	s_waitcnt lgkmcnt(12)
	v_mfma_f32_16x16x32_bf16 v[106:109], v[220:223], v[212:215], v[106:109]
	ds_read_b64_tr_b16 v[186:187], v137 offset:8192
	ds_read_b64_tr_b16 v[188:189], v145 offset:8192
	s_waitcnt lgkmcnt(12)
	v_mfma_f32_16x16x32_bf16 v[110:113], v[220:223], v[194:197], v[110:113]
	s_waitcnt lgkmcnt(10)
	v_mfma_f32_16x16x32_bf16 v[90:93], v[220:223], v[90:93], v[172:175]
	s_waitcnt lgkmcnt(8)
	v_mfma_f32_16x16x32_bf16 v[82:85], v[220:223], v[82:85], v[176:179]
	s_waitcnt lgkmcnt(6)
	v_mfma_f32_16x16x32_bf16 v[86:89], v[220:223], v[86:89], v[182:185]
	s_waitcnt lgkmcnt(4)
	v_mfma_f32_16x16x32_bf16 v[94:97], v[220:223], v[94:97], v[120:123]
	s_waitcnt lgkmcnt(2)
	v_mfma_f32_16x16x32_bf16 v[102:105], v[220:223], v[190:193], v[102:105]
	s_waitcnt lgkmcnt(0)
	v_mfma_f32_16x16x32_bf16 v[98:101], v[220:223], v[186:189], v[98:101]
	s_cbranch_scc1 .LBB0_952
	v_mov_b32_e32 v159, v118
	v_mov_b32_e32 v160, v117
	s_branch .LBB0_928
